# reverse CU order of the filter-tap GEMM units in phase 1 so extra units land on CUs with fewer bias GEMV units
# speedup vs baseline: 1.0035x; 1.0035x over previous
.LBB0_373:
	s_barrier
	s_sub_i32 s5, s6, s5
	s_add_i32 s5, s5, -1
	s_cmpk_gt_i32 s5, 0x43f
	s_cbranch_scc1 .LBB0_377
